# NA phase only: static s_setprio 1 for waves 4-7 (second wave of each SIMD) to de-phase co-resident waves; reset after the NA loop
# baseline (speedup 1.0000x reference)
; #define NA_SLOAD(j) do { const long _k0 = NA_TROW(j); vs0 = *reinterpret_cast<const bf16x8*>(&Vh[(_k0 + sr) * LDP + sc]); vs1 = *reinterpret_cast<const bf16x8*>(&Vh[(_k0 + 32 + sr) * LDP + sc]); \
;     ks0 = *reinterpret_cast<const bf16x8*>(&Kh[(_k0 + sr) * LDP + sc]); ks1 = *reinterpret_cast<const bf16x8*>(&Kh[(_k0 + 32 + sr) * LDP + sc]); } while (0)
; #define NA_SWRITE(b) do { *(bf16x8*)((char*)V_lds + (b) * SHM_V + vst0) = vs0; *(bf16x8*)((char*)V_lds + (b) * SHM_V + vst1) = vs1; const int kc = sc * 2; \
;     *(bf16x8*)((char*)K_lds + (b) * SHM_K + NA_KSWZ(sr, kc)) = ks0; *(bf16x8*)((char*)K_lds + (b) * SHM_K + NA_KSWZ(32 + sr, kc)) = ks1; } while (0)
; template <int LDP, int LDO> ...
;     ...
;   for (int j = 0; j < NT; ++j) {
;     const int b = j & 1;
;     NA_SWRITE(b);
;     if (j + 1 < NT) NA_SLOAD(j + 1);
;     __syncthreads();
; __global__ void __launch_bounds__(NWAVES * 64, 2) fwd_kernel(Args args) {
;     ...
;                 for (int u = F.vcu; u < 512; u += F.G) { const int b = u >> 7, h = (u >> 4) & 7, i = u & 15;
;                     const int klo = i == 0 ? 0 : (i == 15 ? 56 : 4 * i - 4), nband = (i == 0 || i == 15) ? 8 : 12;
;                     na::na_unit<DINP, D>(P, C_QA + 128 * h, C_KA + 128 * h, C_VA + 128 * h, (long)b * SEQ + 256 * i, (long)MLAT + b * CTXL, (long)b * SEQ + 64 * klo, nband, klo, 4 * i,
;                                          MIX, 128 * h, (F.ka->in[I_RPB]) + ((size_t)e * 8 + h) * 15 * 31, (char*)lds + RING_OFF, F.tid); }
.LBB0_700:
	v_readfirstlane_b32 s99, v247
	s_lshr_b32 s99, s99, 8
	s_cmp_lg_u32 s99, 0
	s_cbranch_scc0 .Lna_prio_skip
	s_setprio 1

; __global__ void __launch_bounds__(NWAVES * 64, 2) fwd_kernel(Args args) {
;     ...
;                 for (int u = F.vcu; u < 512; u += F.G) { const int b = u >> 7, h = (u >> 4) & 7, i = u & 15;
;                     const int klo = i == 0 ? 0 : (i == 15 ? 56 : 4 * i - 4), nband = (i == 0 || i == 15) ? 8 : 12;
;                     na::na_unit<DINP, D>(P, C_QA + 128 * h, C_KA + 128 * h, C_VA + 128 * h, (long)b * SEQ + 256 * i, (long)MLAT + b * CTXL, (long)b * SEQ + 64 * klo, nband, klo, 4 * i,
;                                          MIX, 128 * h, (F.ka->in[I_RPB]) + ((size_t)e * 8 + h) * 15 * 31, (char*)lds + RING_OFF, F.tid); }
;             } PHASE_END
.LBB0_733:
	s_setprio 0
	s_mov_b64 s[40:41], -1
